# GLA pass A prologue: all loads of a pair (gate-up, V image, dn, k, q, gate bias) issued before the first wait
# speedup vs baseline: 1.0048x; 1.0027x over previous
.LBB0_334:
	s_and_b32 s5, s5, 3
	v_lshlrev_b32_sdwa v16, v81, v82 dst_sel:DWORD dst_unused:UNUSED_PAD src0_sel:DWORD src1_sel:BYTE_0
	v_and_b32_e32 v83, 63, v82
	s_lshl_b32 s2, s5, 6
	v_and_b32_e32 v0, 0x300, v16
	v_or3_b32 v1, s2, v83, v0
	v_or_b32_sdwa v3, v82, s23 dst_sel:DWORD dst_unused:UNUSED_PAD src0_sel:BYTE_0 src1_sel:DWORD
	v_lshlrev_b32_e32 v2, 2, v1
	v_lshlrev_b32_e32 v1, 2, v3
	v_and_b32_e32 v1, 0x700, v1
	v_or3_b32 v1, v83, v1, s2
	v_or_b32_sdwa v8, v82, s25 dst_sel:DWORD dst_unused:UNUSED_PAD src0_sel:BYTE_0 src1_sel:DWORD
	v_lshlrev_b32_e32 v4, 2, v1
	v_lshlrev_b32_e32 v1, 2, v8
	v_and_b32_e32 v1, 0xb00, v1
	v_or3_b32 v1, v83, v1, s2
	v_or_b32_sdwa v12, v82, s24 dst_sel:DWORD dst_unused:UNUSED_PAD src0_sel:BYTE_0 src1_sel:DWORD
	v_lshlrev_b32_e32 v5, 2, v1
	v_lshlrev_b32_e32 v1, 2, v12
	v_and_b32_e32 v1, 0xf00, v1
	v_or3_b32 v0, v83, v0, s2
	v_or3_b32 v1, v83, v1, s2
	v_lshlrev_b32_e32 v64, 2, v0
	v_lshlrev_b32_e32 v6, 2, v1
	v_lshl_add_u64 v[0:1], s[56:57], 0, v[64:65]
	v_bitop3_b32 v7, v16, s27, v78 bitop3:0xc8
	v_bitop3_b32 v9, v16, s28, v79 bitop3:0xc8
	v_bitop3_b32 v10, v16, s29, v80 bitop3:0xc8
	v_add_co_u32_e32 v0, vcc, s26, v0
	v_or3_b32 v7, v83, v7, s2
	v_or3_b32 v9, v83, v9, s2
	v_or3_b32 v10, v83, v10, s2
	v_addc_co_u32_e32 v1, vcc, 0, v1, vcc
	v_lshlrev_b32_e32 v7, 2, v7
	v_lshlrev_b32_e32 v9, 2, v9
	v_lshlrev_b32_e32 v10, 2, v10
	global_load_dword v202, v2, s[56:57]
	global_load_dword v203, v4, s[56:57]
	global_load_dword v204, v5, s[56:57]
	global_load_dword v205, v6, s[56:57]
	global_load_dword v206, v[0:1], off
	global_load_dword v207, v7, s[56:57]
	global_load_dword v208, v9, s[56:57]
	global_load_dword v209, v10, s[56:57]
	v_lshlrev_b32_e32 v0, 4, v82
	v_bfe_u32 v25, v82, 4, 4
	v_and_b32_e32 v64, 0xf0, v0
	v_add_u32_e32 v0, s0, v25
	v_lshrrev_b32_e32 v26, 4, v3
	v_mad_i64_i32 v[0:1], s[2:3], v0, s30, v[66:67]
	v_add_u32_e32 v2, s0, v26
	v_lshrrev_b32_e32 v27, 4, v8
	s_lshl_b32 s2, s5, 8
	s_mov_b32 s3, s11
	v_mad_i64_i32 v[2:3], s[14:15], v2, s30, v[66:67]
	v_add_u32_e32 v8, s0, v27
	v_lshl_add_u64 v[0:1], v[0:1], 0, s[2:3]
	v_lshl_add_u64 v[2:3], v[2:3], 0, s[2:3]
	v_mad_i64_i32 v[8:9], s[14:15], v8, s30, v[66:67]
	v_lshl_add_u64 v[0:1], v[0:1], 0, v[64:65]
	v_lshl_add_u64 v[4:5], v[2:3], 0, v[64:65]
	v_lshl_add_u64 v[8:9], v[8:9], 0, s[2:3]
	v_lshrrev_b32_e32 v28, 4, v12
	global_load_dwordx4 v[210:213], v[0:1], off offset:1024
	s_nop 0
	global_load_dwordx4 v[214:217], v[4:5], off offset:1024
	v_lshl_add_u64 v[8:9], v[8:9], 0, v[64:65]
	v_add_u32_e32 v12, s0, v28
	global_load_dwordx4 v[218:221], v[8:9], off offset:1024
	v_mad_i64_i32 v[12:13], s[14:15], v12, s30, v[66:67]
	v_lshl_add_u64 v[12:13], v[12:13], 0, s[2:3]
	v_lshl_add_u64 v[12:13], v[12:13], 0, v[64:65]
	global_load_dwordx4 v[222:225], v[12:13], off offset:1024
	s_lshr_b32 s3, s37, 8
	s_mul_i32 s3, s3, 0xd000
	s_add_i32 s43, s3, 0
	v_add_u32_e32 v226, s43, v16
	s_lshl_b32 s14, s5, 7
	s_mov_b32 s15, s11
	v_add_u32_e32 v227, s43, v64
	v_mad_u32_u24 v228, v25, s31, v227
	v_mad_u32_u24 v229, v26, s31, v227
	v_mad_u32_u24 v230, v27, s31, v227
	v_mad_u32_u24 v231, v28, s31, v227
	v_add_u32_e32 v16, s0, v83
	s_lshr_b32 s0, s37, 2
	s_and_b32 s0, s0, 48
	v_ashrrev_i32_e32 v17, 31, v16
	s_lshl_b32 s10, s0, 1
	v_lshlrev_b64 v[0:1], 7, v[16:17]
	v_mad_i64_i32 v[16:17], s[16:17], v16, s30, v[66:67]
	s_cmp_gt_i32 s36, 3
	s_cselect_b64 s[16:17], -1, 0
	s_and_b64 s[38:39], s[16:17], exec
	s_cselect_b32 s38, 0, 0x200
	s_mov_b32 s39, s11
	v_lshl_add_u64 v[18:19], v[16:17], 0, s[14:15]
	v_lshl_add_u64 v[16:17], v[16:17], 0, s[38:39]
	s_lshl_b32 s3, s4, 2
	v_lshl_add_u64 v[16:17], v[16:17], 0, s[14:15]
	s_or_b32 s47, s3, s5
	s_lshl_b32 s14, s0, 2
	s_lshl_b32 s42, s47, 1
	s_add_i32 s46, s43, s14
	s_add_u32 s38, s13, s14
	s_addc_u32 s39, s18, 0
	s_add_u32 s4, s58, s2
	v_lshl_add_u64 v[12:13], s[8:9], 0, v[0:1]
	v_lshl_add_u64 v[18:19], v[18:19], 0, s[10:11]
	v_lshl_add_u64 v[40:41], v[16:17], 0, s[10:11]
	s_addc_u32 s5, s59, 0
	v_mov_b32_e32 v52, s14
	global_load_dwordx4 v[24:27], v[12:13], off offset:48
	global_load_dwordx4 v[28:31], v[12:13], off offset:32
	global_load_dwordx4 v[32:35], v[12:13], off offset:16
	global_load_dwordx4 v[36:39], v[12:13], off
	global_load_dwordx4 v[0:3], v[12:13], off offset:112
	global_load_dwordx4 v[4:7], v[12:13], off offset:96
	global_load_dwordx4 v[8:11], v[12:13], off offset:80
	s_nop 0
	global_load_dwordx4 v[12:15], v[12:13], off offset:64
	s_nop 0
	global_load_dwordx4 v[20:23], v[18:19], off offset:528
	global_load_dwordx4 v[44:47], v[18:19], off offset:512
	s_nop 0
	global_load_dwordx4 v[16:19], v[40:41], off offset:16
	s_nop 0
	global_load_dwordx4 v[40:43], v[40:41], off
	global_load_dwordx4 v[100:103], v52, s[4:5]
	global_load_dwordx4 v[104:107], v52, s[4:5] offset:16
	global_load_dwordx4 v[108:111], v52, s[4:5] offset:1024
	global_load_dwordx4 v[112:115], v52, s[4:5] offset:1040
	global_load_dwordx4 v[116:119], v52, s[4:5] offset:32
	global_load_dwordx4 v[120:123], v52, s[4:5] offset:48
	global_load_dwordx4 v[124:127], v52, s[4:5] offset:1056
	global_load_dwordx4 v[128:131], v52, s[4:5] offset:1072
	s_waitcnt vmcnt(20)
	v_mul_f32_e32 v202, 0x3fb8aa3b, v202
	v_mul_f32_e32 v203, 0x3fb8aa3b, v203
	v_mul_f32_e32 v204, 0x3fb8aa3b, v204
	v_mul_f32_e32 v205, 0x3fb8aa3b, v205
	v_mul_f32_e32 v206, 0x3fb8aa3b, v206
	v_mul_f32_e32 v207, 0x3fb8aa3b, v207
	v_mul_f32_e32 v208, 0x3fb8aa3b, v208
	v_mul_f32_e32 v209, 0x3fb8aa3b, v209
	ds_write2st64_b32 v226, v202, v203 offset1:4
	ds_write2st64_b32 v226, v204, v205 offset0:8 offset1:12
	ds_write2st64_b32 v226, v206, v207 offset0:16 offset1:20
	ds_write2st64_b32 v226, v208, v209 offset0:24 offset1:28
	ds_write_b128 v228, v[210:213] offset:32768
	ds_write_b128 v229, v[214:217] offset:32768
	ds_write_b128 v230, v[218:221] offset:32768
	ds_write_b128 v231, v[222:225] offset:32768
	s_waitcnt lgkmcnt(0)
	s_barrier
	s_sub_i32 s1, s1, s36
	s_mul_i32 s45, s42, 0x84
	s_mov_b32 s44, 0
	s_bfe_u32 s2, s37, 0x20006
	s_lshl_b32 s3, s2, 5
	s_add_i32 s10, s43, s3
	s_addk_i32 s10, 0x2000
	v_mul_u32_u24_e32 v63, 0xc0, v83
	v_add_u32_e32 v61, s10, v63
	v_mov_b32_e32 v60, s46
	v_lshlrev_b32_e32 v63, 7, v83
	v_add_u32_e32 v62, s3, v63
	s_lshl_b32 s4, s47, 7
	s_add_i32 s4, s4, s36
	s_add_i32 s4, s4, -4
	s_lshl_b32 s4, s4, 15
	s_add_u32 s4, s19, s4
	s_addc_u32 s5, s20, 0
	s_mov_b32 s47, 0x42ac0000
	v_cmp_eq_u32_e64 s[16:17], 0, v83
	s_waitcnt vmcnt(0)
	v_lshlrev_b32_e32 v202, 16, v44
	v_and_b32_e32 v203, 0xffff0000, v44
	v_lshlrev_b32_e32 v204, 16, v45
	v_and_b32_e32 v205, 0xffff0000, v45
	v_lshlrev_b32_e32 v206, 16, v46
	v_and_b32_e32 v207, 0xffff0000, v46
	v_lshlrev_b32_e32 v208, 16, v47
	v_and_b32_e32 v209, 0xffff0000, v47
	v_lshlrev_b32_e32 v210, 16, v40
	v_and_b32_e32 v211, 0xffff0000, v40
	v_lshlrev_b32_e32 v212, 16, v41
	v_and_b32_e32 v213, 0xffff0000, v41
	v_lshlrev_b32_e32 v214, 16, v42
	v_and_b32_e32 v215, 0xffff0000, v42
	v_lshlrev_b32_e32 v216, 16, v43
	v_and_b32_e32 v217, 0xffff0000, v43
	ds_read_b128 v[132:135], v60
	ds_read_b128 v[136:139], v60 offset:16
	ds_read_b128 v[140:143], v60 offset:256
	ds_read_b128 v[144:147], v60 offset:272
	ds_read_b128 v[148:151], v60 offset:512
	ds_read_b128 v[152:155], v60 offset:528
	ds_read_b128 v[156:159], v60 offset:768
	ds_read_b128 v[160:163], v60 offset:784
	ds_read_b128 v[164:167], v60 offset:1024
	ds_read_b128 v[168:171], v60 offset:1040
	ds_read_b128 v[172:175], v60 offset:1280
	ds_read_b128 v[176:179], v60 offset:1296
	v_pk_mul_f32 v[84:85], v[100:101], s[12:13] op_sel_hi:[1,0]
	v_pk_mul_f32 v[86:87], v[102:103], s[12:13] op_sel_hi:[1,0]
	v_pk_mul_f32 v[88:89], v[104:105], s[12:13] op_sel_hi:[1,0]
	v_pk_mul_f32 v[90:91], v[106:107], s[12:13] op_sel_hi:[1,0]
	s_waitcnt lgkmcnt(11)
	v_pk_fma_f32 v[84:85], v[36:37], v[132:133], v[84:85] op_sel_hi:[0,1,1]
	v_pk_fma_f32 v[86:87], v[36:37], v[134:135], v[86:87] op_sel_hi:[0,1,1]
	ds_read_b128 v[132:135], v60 offset:1536
	s_waitcnt lgkmcnt(11)
	v_pk_fma_f32 v[88:89], v[36:37], v[136:137], v[88:89] op_sel_hi:[0,1,1]
	v_pk_fma_f32 v[90:91], v[36:37], v[138:139], v[90:91] op_sel_hi:[0,1,1]
	ds_read_b128 v[136:139], v60 offset:1552
	s_waitcnt lgkmcnt(11)
	v_pk_fma_f32 v[84:85], v[36:37], v[140:141], v[84:85] op_sel:[1,0,0]
	v_pk_fma_f32 v[86:87], v[36:37], v[142:143], v[86:87] op_sel:[1,0,0]
	ds_read_b128 v[140:143], v60 offset:1792
	s_waitcnt lgkmcnt(11)
	v_pk_fma_f32 v[88:89], v[36:37], v[144:145], v[88:89] op_sel:[1,0,0]
	v_pk_fma_f32 v[90:91], v[36:37], v[146:147], v[90:91] op_sel:[1,0,0]
	ds_read_b128 v[144:147], v60 offset:1808
	s_waitcnt lgkmcnt(11)
	v_pk_fma_f32 v[84:85], v[38:39], v[148:149], v[84:85] op_sel_hi:[0,1,1]
	v_pk_fma_f32 v[86:87], v[38:39], v[150:151], v[86:87] op_sel_hi:[0,1,1]
	ds_read_b128 v[148:151], v60 offset:2048
	s_waitcnt lgkmcnt(11)
	v_pk_fma_f32 v[88:89], v[38:39], v[152:153], v[88:89] op_sel_hi:[0,1,1]
	v_pk_fma_f32 v[90:91], v[38:39], v[154:155], v[90:91] op_sel_hi:[0,1,1]
	ds_read_b128 v[152:155], v60 offset:2064
	s_waitcnt lgkmcnt(11)
	v_pk_fma_f32 v[84:85], v[38:39], v[156:157], v[84:85] op_sel:[1,0,0]
	v_pk_fma_f32 v[86:87], v[38:39], v[158:159], v[86:87] op_sel:[1,0,0]
	ds_read_b128 v[156:159], v60 offset:2304
	s_waitcnt lgkmcnt(11)
	v_pk_fma_f32 v[88:89], v[38:39], v[160:161], v[88:89] op_sel:[1,0,0]
	v_pk_fma_f32 v[90:91], v[38:39], v[162:163], v[90:91] op_sel:[1,0,0]
	ds_read_b128 v[160:163], v60 offset:2320
	s_waitcnt lgkmcnt(11)
	v_pk_fma_f32 v[84:85], v[32:33], v[164:165], v[84:85] op_sel_hi:[0,1,1]
	v_pk_fma_f32 v[86:87], v[32:33], v[166:167], v[86:87] op_sel_hi:[0,1,1]
	ds_read_b128 v[164:167], v60 offset:2560
	s_waitcnt lgkmcnt(11)
	v_pk_fma_f32 v[88:89], v[32:33], v[168:169], v[88:89] op_sel_hi:[0,1,1]
	v_pk_fma_f32 v[90:91], v[32:33], v[170:171], v[90:91] op_sel_hi:[0,1,1]
	ds_read_b128 v[168:171], v60 offset:2576
	s_waitcnt lgkmcnt(11)
	v_pk_fma_f32 v[84:85], v[32:33], v[172:173], v[84:85] op_sel:[1,0,0]
	v_pk_fma_f32 v[86:87], v[32:33], v[174:175], v[86:87] op_sel:[1,0,0]
	ds_read_b128 v[172:175], v60 offset:2816
	s_waitcnt lgkmcnt(11)
	v_pk_fma_f32 v[88:89], v[32:33], v[176:177], v[88:89] op_sel:[1,0,0]
	v_pk_fma_f32 v[90:91], v[32:33], v[178:179], v[90:91] op_sel:[1,0,0]
	ds_read_b128 v[176:179], v60 offset:2832
	s_waitcnt lgkmcnt(11)
	v_pk_fma_f32 v[84:85], v[34:35], v[132:133], v[84:85] op_sel_hi:[0,1,1]
	v_pk_fma_f32 v[86:87], v[34:35], v[134:135], v[86:87] op_sel_hi:[0,1,1]
	ds_read_b128 v[132:135], v60 offset:3072
	s_waitcnt lgkmcnt(11)
	v_pk_fma_f32 v[88:89], v[34:35], v[136:137], v[88:89] op_sel_hi:[0,1,1]
	v_pk_fma_f32 v[90:91], v[34:35], v[138:139], v[90:91] op_sel_hi:[0,1,1]
	ds_read_b128 v[136:139], v60 offset:3088
	s_waitcnt lgkmcnt(11)
	v_pk_fma_f32 v[84:85], v[34:35], v[140:141], v[84:85] op_sel:[1,0,0]
	v_pk_fma_f32 v[86:87], v[34:35], v[142:143], v[86:87] op_sel:[1,0,0]
	ds_read_b128 v[140:143], v60 offset:3328
	s_waitcnt lgkmcnt(11)
	v_pk_fma_f32 v[88:89], v[34:35], v[144:145], v[88:89] op_sel:[1,0,0]
	v_pk_fma_f32 v[90:91], v[34:35], v[146:147], v[90:91] op_sel:[1,0,0]
	ds_read_b128 v[144:147], v60 offset:3344
	s_waitcnt lgkmcnt(11)
	v_pk_fma_f32 v[84:85], v[28:29], v[148:149], v[84:85] op_sel_hi:[0,1,1]
	v_pk_fma_f32 v[86:87], v[28:29], v[150:151], v[86:87] op_sel_hi:[0,1,1]
	ds_read_b128 v[148:151], v60 offset:3584
	s_waitcnt lgkmcnt(11)
	v_pk_fma_f32 v[88:89], v[28:29], v[152:153], v[88:89] op_sel_hi:[0,1,1]
	v_pk_fma_f32 v[90:91], v[28:29], v[154:155], v[90:91] op_sel_hi:[0,1,1]
	ds_read_b128 v[152:155], v60 offset:3600
	s_waitcnt lgkmcnt(11)
	v_pk_fma_f32 v[84:85], v[28:29], v[156:157], v[84:85] op_sel:[1,0,0]
	v_pk_fma_f32 v[86:87], v[28:29], v[158:159], v[86:87] op_sel:[1,0,0]
	ds_read_b128 v[156:159], v60 offset:3840
	s_waitcnt lgkmcnt(11)
	v_pk_fma_f32 v[88:89], v[28:29], v[160:161], v[88:89] op_sel:[1,0,0]
	v_pk_fma_f32 v[90:91], v[28:29], v[162:163], v[90:91] op_sel:[1,0,0]
	ds_read_b128 v[160:163], v60 offset:3856
	s_waitcnt lgkmcnt(11)
	v_pk_fma_f32 v[84:85], v[30:31], v[164:165], v[84:85] op_sel_hi:[0,1,1]
	v_pk_fma_f32 v[86:87], v[30:31], v[166:167], v[86:87] op_sel_hi:[0,1,1]
	s_waitcnt lgkmcnt(10)
	v_pk_fma_f32 v[88:89], v[30:31], v[168:169], v[88:89] op_sel_hi:[0,1,1]
	v_pk_fma_f32 v[90:91], v[30:31], v[170:171], v[90:91] op_sel_hi:[0,1,1]
	s_waitcnt lgkmcnt(9)
	v_pk_fma_f32 v[84:85], v[30:31], v[172:173], v[84:85] op_sel:[1,0,0]
	v_pk_fma_f32 v[86:87], v[30:31], v[174:175], v[86:87] op_sel:[1,0,0]
	s_waitcnt lgkmcnt(8)
	v_pk_fma_f32 v[88:89], v[30:31], v[176:177], v[88:89] op_sel:[1,0,0]
	v_pk_fma_f32 v[90:91], v[30:31], v[178:179], v[90:91] op_sel:[1,0,0]
	s_waitcnt lgkmcnt(7)
	v_pk_fma_f32 v[84:85], v[24:25], v[132:133], v[84:85] op_sel_hi:[0,1,1]
	v_pk_fma_f32 v[86:87], v[24:25], v[134:135], v[86:87] op_sel_hi:[0,1,1]
	s_waitcnt lgkmcnt(6)
	v_pk_fma_f32 v[88:89], v[24:25], v[136:137], v[88:89] op_sel_hi:[0,1,1]
	v_pk_fma_f32 v[90:91], v[24:25], v[138:139], v[90:91] op_sel_hi:[0,1,1]
	s_waitcnt lgkmcnt(5)
	v_pk_fma_f32 v[84:85], v[24:25], v[140:141], v[84:85] op_sel:[1,0,0]
	v_pk_fma_f32 v[86:87], v[24:25], v[142:143], v[86:87] op_sel:[1,0,0]
	s_waitcnt lgkmcnt(4)
	v_pk_fma_f32 v[88:89], v[24:25], v[144:145], v[88:89] op_sel:[1,0,0]
	v_pk_fma_f32 v[90:91], v[24:25], v[146:147], v[90:91] op_sel:[1,0,0]
	s_waitcnt lgkmcnt(3)
	v_pk_fma_f32 v[84:85], v[26:27], v[148:149], v[84:85] op_sel_hi:[0,1,1]
	v_pk_fma_f32 v[86:87], v[26:27], v[150:151], v[86:87] op_sel_hi:[0,1,1]
	s_waitcnt lgkmcnt(2)
	v_pk_fma_f32 v[88:89], v[26:27], v[152:153], v[88:89] op_sel_hi:[0,1,1]
	v_pk_fma_f32 v[90:91], v[26:27], v[154:155], v[90:91] op_sel_hi:[0,1,1]
	s_waitcnt lgkmcnt(1)
	v_pk_fma_f32 v[84:85], v[26:27], v[156:157], v[84:85] op_sel:[1,0,0]
	v_pk_fma_f32 v[86:87], v[26:27], v[158:159], v[86:87] op_sel:[1,0,0]
	s_waitcnt lgkmcnt(0)
	v_pk_fma_f32 v[88:89], v[26:27], v[160:161], v[88:89] op_sel:[1,0,0]
	v_pk_fma_f32 v[90:91], v[26:27], v[162:163], v[90:91] op_sel:[1,0,0]
	v_exp_f32_e64 v242, -|v84|
	v_exp_f32_e64 v243, -|v85|
	v_exp_f32_e64 v244, -|v86|
	v_exp_f32_e64 v245, -|v87|
	v_exp_f32_e64 v246, -|v88|
	v_exp_f32_e64 v247, -|v89|
	v_exp_f32_e64 v248, -|v90|
	v_exp_f32_e64 v249, -|v91|
	v_add_f32_e32 v242, 1.0, v242
	v_add_f32_e32 v243, 1.0, v243
	v_add_f32_e32 v244, 1.0, v244
	v_add_f32_e32 v245, 1.0, v245
	v_add_f32_e32 v246, 1.0, v246
	v_add_f32_e32 v247, 1.0, v247
	v_add_f32_e32 v248, 1.0, v248
	v_add_f32_e32 v249, 1.0, v249
	v_log_f32_e32 v242, v242
	v_log_f32_e32 v243, v243
	v_log_f32_e32 v244, v244
	v_log_f32_e32 v245, v245
	v_log_f32_e32 v246, v246
	v_log_f32_e32 v247, v247
	v_log_f32_e32 v248, v248
	v_log_f32_e32 v249, v249
	v_min_f32_e32 v92, 0, v84
	v_min_f32_e32 v93, 0, v85
	v_min_f32_e32 v94, 0, v86
	v_min_f32_e32 v95, 0, v87
	v_min_f32_e32 v96, 0, v88
	v_min_f32_e32 v97, 0, v89
	v_min_f32_e32 v98, 0, v90
	v_min_f32_e32 v99, 0, v91
	v_sub_f32_e32 v92, v92, v242
	v_sub_f32_e32 v93, v93, v243
	v_sub_f32_e32 v94, v94, v244
	v_sub_f32_e32 v95, v95, v245
	v_sub_f32_e32 v96, v96, v246
	v_sub_f32_e32 v97, v97, v247
	v_sub_f32_e32 v98, v98, v248
	v_sub_f32_e32 v99, v99, v249
	v_mul_f32_e32 v92, 0x3d800000, v92
	v_mul_f32_e32 v93, 0x3d800000, v93
	v_mul_f32_e32 v94, 0x3d800000, v94
	v_mul_f32_e32 v95, 0x3d800000, v95
	v_mul_f32_e32 v96, 0x3d800000, v96
	v_mul_f32_e32 v97, 0x3d800000, v97
	v_mul_f32_e32 v98, 0x3d800000, v98
	v_mul_f32_e32 v99, 0x3d800000, v99
	v_add_f32_dpp v180, v92, v92 row_shr:1 row_mask:0xf bank_mask:0xf bound_ctrl:1
	v_add_f32_dpp v181, v93, v93 row_shr:1 row_mask:0xf bank_mask:0xf bound_ctrl:1
	v_add_f32_dpp v182, v94, v94 row_shr:1 row_mask:0xf bank_mask:0xf bound_ctrl:1
	v_add_f32_dpp v183, v95, v95 row_shr:1 row_mask:0xf bank_mask:0xf bound_ctrl:1
	v_add_f32_dpp v184, v96, v96 row_shr:1 row_mask:0xf bank_mask:0xf bound_ctrl:1
	v_add_f32_dpp v185, v97, v97 row_shr:1 row_mask:0xf bank_mask:0xf bound_ctrl:1
	v_add_f32_dpp v186, v98, v98 row_shr:1 row_mask:0xf bank_mask:0xf bound_ctrl:1
	v_add_f32_dpp v187, v99, v99 row_shr:1 row_mask:0xf bank_mask:0xf bound_ctrl:1
	v_add_f32_dpp v180, v180, v180 row_shr:2 row_mask:0xf bank_mask:0xf bound_ctrl:1
	v_add_f32_dpp v181, v181, v181 row_shr:2 row_mask:0xf bank_mask:0xf bound_ctrl:1
	v_add_f32_dpp v182, v182, v182 row_shr:2 row_mask:0xf bank_mask:0xf bound_ctrl:1
	v_add_f32_dpp v183, v183, v183 row_shr:2 row_mask:0xf bank_mask:0xf bound_ctrl:1
	v_add_f32_dpp v184, v184, v184 row_shr:2 row_mask:0xf bank_mask:0xf bound_ctrl:1
	v_add_f32_dpp v185, v185, v185 row_shr:2 row_mask:0xf bank_mask:0xf bound_ctrl:1
	v_add_f32_dpp v186, v186, v186 row_shr:2 row_mask:0xf bank_mask:0xf bound_ctrl:1
	v_add_f32_dpp v187, v187, v187 row_shr:2 row_mask:0xf bank_mask:0xf bound_ctrl:1
	v_add_f32_dpp v180, v180, v180 row_shr:4 row_mask:0xf bank_mask:0xf bound_ctrl:1
	v_add_f32_dpp v181, v181, v181 row_shr:4 row_mask:0xf bank_mask:0xf bound_ctrl:1
	v_add_f32_dpp v182, v182, v182 row_shr:4 row_mask:0xf bank_mask:0xf bound_ctrl:1
	v_add_f32_dpp v183, v183, v183 row_shr:4 row_mask:0xf bank_mask:0xf bound_ctrl:1
	v_add_f32_dpp v184, v184, v184 row_shr:4 row_mask:0xf bank_mask:0xf bound_ctrl:1
	v_add_f32_dpp v185, v185, v185 row_shr:4 row_mask:0xf bank_mask:0xf bound_ctrl:1
	v_add_f32_dpp v186, v186, v186 row_shr:4 row_mask:0xf bank_mask:0xf bound_ctrl:1
	v_add_f32_dpp v187, v187, v187 row_shr:4 row_mask:0xf bank_mask:0xf bound_ctrl:1
	v_add_f32_dpp v180, v180, v180 row_shr:8 row_mask:0xf bank_mask:0xf bound_ctrl:1
	v_add_f32_dpp v181, v181, v181 row_shr:8 row_mask:0xf bank_mask:0xf bound_ctrl:1
	v_add_f32_dpp v182, v182, v182 row_shr:8 row_mask:0xf bank_mask:0xf bound_ctrl:1
	v_add_f32_dpp v183, v183, v183 row_shr:8 row_mask:0xf bank_mask:0xf bound_ctrl:1
	v_add_f32_dpp v184, v184, v184 row_shr:8 row_mask:0xf bank_mask:0xf bound_ctrl:1
	v_add_f32_dpp v185, v185, v185 row_shr:8 row_mask:0xf bank_mask:0xf bound_ctrl:1
	v_add_f32_dpp v186, v186, v186 row_shr:8 row_mask:0xf bank_mask:0xf bound_ctrl:1
	v_add_f32_dpp v187, v187, v187 row_shr:8 row_mask:0xf bank_mask:0xf bound_ctrl:1
	v_add_f32_dpp v180, v180, v180 row_bcast:15 row_mask:0xa bank_mask:0xf
	v_add_f32_dpp v181, v181, v181 row_bcast:15 row_mask:0xa bank_mask:0xf
	v_add_f32_dpp v182, v182, v182 row_bcast:15 row_mask:0xa bank_mask:0xf
	v_add_f32_dpp v183, v183, v183 row_bcast:15 row_mask:0xa bank_mask:0xf
	v_add_f32_dpp v184, v184, v184 row_bcast:15 row_mask:0xa bank_mask:0xf
	v_add_f32_dpp v185, v185, v185 row_bcast:15 row_mask:0xa bank_mask:0xf
	v_add_f32_dpp v186, v186, v186 row_bcast:15 row_mask:0xa bank_mask:0xf
	v_add_f32_dpp v187, v187, v187 row_bcast:15 row_mask:0xa bank_mask:0xf
	v_add_f32_dpp v180, v180, v180 row_bcast:31 row_mask:0xc bank_mask:0xf
	v_add_f32_dpp v181, v181, v181 row_bcast:31 row_mask:0xc bank_mask:0xf
	v_add_f32_dpp v182, v182, v182 row_bcast:31 row_mask:0xc bank_mask:0xf
	v_add_f32_dpp v183, v183, v183 row_bcast:31 row_mask:0xc bank_mask:0xf
	v_add_f32_dpp v184, v184, v184 row_bcast:31 row_mask:0xc bank_mask:0xf
	v_add_f32_dpp v185, v185, v185 row_bcast:31 row_mask:0xc bank_mask:0xf
	v_add_f32_dpp v186, v186, v186 row_bcast:31 row_mask:0xc bank_mask:0xf
	v_add_f32_dpp v187, v187, v187 row_bcast:31 row_mask:0xc bank_mask:0xf
	v_readlane_b32 s0, v180, 63
	v_readlane_b32 s10, v181, 63
	v_readlane_b32 s14, v182, 63
	v_readlane_b32 s15, v183, 63
	v_exp_f32_e32 v234, s0
	v_exp_f32_e32 v235, s10
	v_exp_f32_e32 v236, s14
	v_exp_f32_e32 v237, s15
	v_readlane_b32 s0, v184, 63
	v_readlane_b32 s10, v185, 63
	v_readlane_b32 s14, v186, 63
	v_readlane_b32 s15, v187, 63
	v_exp_f32_e32 v238, s0
	v_exp_f32_e32 v239, s10
	v_exp_f32_e32 v240, s14
	v_exp_f32_e32 v241, s15
	v_min_f32_e64 v242, -v180, s47
	v_min_f32_e64 v243, -v181, s47
	v_min_f32_e64 v244, -v182, s47
	v_min_f32_e64 v245, -v183, s47
	v_min_f32_e64 v246, -v184, s47
	v_min_f32_e64 v247, -v185, s47
	v_min_f32_e64 v248, -v186, s47
	v_min_f32_e64 v249, -v187, s47
	v_exp_f32_e32 v226, v242
	v_exp_f32_e32 v227, v243
	v_exp_f32_e32 v228, v244
	v_exp_f32_e32 v229, v245
	v_exp_f32_e32 v230, v246
	v_exp_f32_e32 v231, v247
	v_exp_f32_e32 v232, v248
	v_exp_f32_e32 v233, v249
	v_exp_f32_e32 v218, v180
	v_exp_f32_e32 v219, v181
	v_exp_f32_e32 v220, v182
	v_exp_f32_e32 v221, v183
	v_exp_f32_e32 v222, v184
	v_exp_f32_e32 v223, v185
	v_exp_f32_e32 v224, v186
	v_exp_f32_e32 v225, v187
	v_pk_mul_f32 v[242:243], v[202:203], v[226:227]
	v_pk_mul_f32 v[244:245], v[204:205], v[228:229]
	v_pk_mul_f32 v[246:247], v[206:207], v[230:231]
	v_pk_mul_f32 v[248:249], v[208:209], v[232:233]
	v_pk_mul_f32 v[92:93], v[242:243], v[234:235]
	v_pk_mul_f32 v[94:95], v[244:245], v[236:237]
	v_pk_mul_f32 v[96:97], v[246:247], v[238:239]
	v_pk_mul_f32 v[98:99], v[248:249], v[240:241]
	v_cvt_pk_bf16_f32 v48, v92, v93
	v_cvt_pk_bf16_f32 v49, v94, v95
	v_cvt_pk_bf16_f32 v50, v96, v97
	v_cvt_pk_bf16_f32 v51, v98, v99
	ds_write_b128 v61, v[48:51] offset:0
	s_add_i32 s48, s45, s36
	s_lshl_b32 s48, s48, 8
	s_add_u32 s48, s38, s48
	s_addc_u32 s49, s39, 0
	s_mov_b64 exec, s[16:17]
	global_store_dwordx4 v65, v[234:237], s[48:49]
	global_store_dwordx4 v65, v[238:241], s[48:49] offset:16
	s_mov_b64 exec, -1
	s_cmp_gt_i32 s36, 3
	s_cbranch_scc0 .Lgla_noq_0
	v_pk_mul_f32 v[218:219], v[210:211], v[218:219]
	v_pk_mul_f32 v[220:221], v[212:213], v[220:221]
	v_pk_mul_f32 v[222:223], v[214:215], v[222:223]
	v_pk_mul_f32 v[224:225], v[216:217], v[224:225]
	v_cvt_pk_bf16_f32 v52, v218, v219
	v_cvt_pk_bf16_f32 v53, v220, v221
	v_cvt_pk_bf16_f32 v54, v222, v223
	v_cvt_pk_bf16_f32 v55, v224, v225
	v_cvt_pk_bf16_f32 v56, v242, v243
	v_cvt_pk_bf16_f32 v57, v244, v245
	v_cvt_pk_bf16_f32 v58, v246, v247
	v_cvt_pk_bf16_f32 v59, v248, v249
	s_add_u32 s48, s4, 0x0
	s_addc_u32 s49, s5, 0
	global_store_dwordx4 v62, v[52:55], s[48:49]
	s_add_u32 s48, s4, 0x2000
	s_addc_u32 s49, s5, 0
	global_store_dwordx4 v62, v[56:59], s[48:49]
